# combo14 + mixer work-queue ticket of the next item requested while the current item runs (not behind recurrence units)
# baseline (speedup 1.0000x reference)
; __global__ void __launch_bounds__(512, 2) fwd(Args a) {
;     ...
;                 unsigned* qh = ctl + CW_QUEUE + 64 * (l * 2 + half);
;                 unsigned* pre_cnt = ctl + CW_QUEUE + 64 * (8 + l * 2 + half); unsigned* scan_cnt = ctl + CW_QUEUE + 64 * (16 + l * 2 + half);
;                 for (;;) {
;                     if (tid_ == 0) MISC[16] = __hip_atomic_fetch_add(qh, 1u, __ATOMIC_RELAXED, __HIP_MEMORY_SCOPE_AGENT);
.LBB0_488:
	s_andn2_b64 vcc, exec, s[0:1]
	s_cbranch_vccnz .LBB0_805
	s_lshl_b32 s0, s56, 6
	v_readlane_b32 s4, v255, 12
	s_or_b32 s60, s0, s4
	s_lshl_b64 s[0:1], s[60:61], 2
	v_readlane_b32 s4, v254, 2
	s_add_u32 s34, s4, s0
	v_readlane_b32 s0, v254, 3
	s_addc_u32 s35, s0, s1
	v_readlane_b32 s5, v255, 13
	s_add_u32 s4, s34, 0x1000
	s_addc_u32 s5, s35, 0
	v_cmp_eq_u32_e64 s[40:41], 0, v214
	v_mov_b32_e32 v213, 0
	s_branch .LBB0_494

; __global__ void __launch_bounds__(512, 2) fwd(Args a) {
;     ...
;                 for (;;) {
;                     if (tid_ == 0) MISC[16] = __hip_atomic_fetch_add(qh, 1u, __ATOMIC_RELAXED, __HIP_MEMORY_SCOPE_AGENT);
;                     __syncthreads();
.LBB0_494:
	s_and_saveexec_b64 s[0:1], s[40:41]
	s_cbranch_execz .LBB0_498
	s_mov_b64 s[12:13], exec
	s_waitcnt vmcnt(0)
	v_mbcnt_lo_u32_b32 v0, s12, 0
	v_mbcnt_hi_u32_b32 v0, s13, v0
	v_cmp_eq_u32_e32 vcc, 0, v0
	s_and_saveexec_b64 s[10:11], vcc
	s_cbranch_execz .LBB0_497
	v_readfirstlane_b32 s6, v213
	s_cmp_lg_u32 s6, 0
	s_cbranch_scc0 .Lqpf_fetch
	v_mov_b32_e32 v1, v212
	s_branch .LBB0_497
.Lqpf_fetch:
	s_bcnt1_i32_b64 s6, s[12:13]
	v_mov_b32_e32 v1, s6
	global_atomic_add v1, v169, v1, s[34:35] sc0

; __global__ void __launch_bounds__(512, 2) fwd(Args a) {
;     ...
;                     if (tid_ == 0) MISC[16] = __hip_atomic_fetch_add(qh, 1u, __ATOMIC_RELAXED, __HIP_MEMORY_SCOPE_AGENT);
;                     __syncthreads();
;                     const int item = (int)MISC[16];
;                     __syncthreads();
;                     if (item >= Q_POST) break;
.LBB0_498:
	s_or_b64 exec, exec, s[0:1]
	s_waitcnt vmcnt(0)
	v_mov_b32_e32 v0, s54
	s_waitcnt vmcnt(0) lgkmcnt(0)
	s_barrier
	ds_read_b32 v0, v0
	s_movk_i32 s0, 0x83f
	s_waitcnt lgkmcnt(0)
	s_barrier
	v_cmp_lt_i32_e32 vcc, s0, v0
	v_readfirstlane_b32 s56, v0
	s_mov_b64 s[0:1], -1
	s_cbranch_vccnz .LBB0_493
	v_mov_b32_e32 v213, 0
	s_add_i32 s6, s56, 0xfffffd00
	s_cmp_lt_u32 s6, 64
	s_cbranch_scc1 .Lqpf_skip
	v_mov_b32_e32 v213, 1
	s_and_saveexec_b64 s[10:11], s[40:41]
	s_cbranch_execz .Lqpf_x
	v_mov_b32_e32 v212, 1
	global_atomic_add v212, v169, v212, s[34:35] sc0

; __global__ void __launch_bounds__(512, 2) fwd(Args a) {
;     ...
;                     if (item >= Q_POST) break;
;                     int t2 = tid_; asm volatile("" : "+v"(t2)); const int l2 = t2 & 63, w2 = __builtin_amdgcn_readfirstlane(t2 >> 6);
;                     if (item < Q_PRE) { phase_pre(UB, UC, sb, l, in.lb_logits, in.gla_b + l * 512, item * 16 + w2, item * 16 + 16, 8, l2); item_publish(pre_cnt, t2); }
;                     else if (item < Q_PRE + 32) { const int id = item - Q_PRE; scan_unit(lds, UB, UC, sb, pre_cnt, Q_PRE, scan_cnt, 0, id >> 3, id & 7, 0, t2, w2, l2); }
;                     else if (item < Q_SCAN) { const int id = item - Q_PRE - 32; scan_unit(lds, UB, UC, sb, pre_cnt, Q_PRE, scan_cnt, 1, id >> 3, (id >> 1) & 3, id & 1, t2, w2, l2); }
;                     else if (item < Q_ATT) { const int id = item - Q_SCAN, qb = 31 - ((id & 255) >> 3), bh = (id >> 8) * 8 + (id & 7);
;                         attn_unit(lds, UA, Y, bh >> 3, bh & 7, qb, in.qk_gains + l * 128, in.rel_bias, in.diff_lambda + l * 256, in.diff_out_gain + l * 128, lam_init, t2, w2, l2); }
;                     else { const int id = item - Q_ATT; item_wait(scan_cnt, 64u, t2); phase_post(UB, UC, Y, in.hgrn_gain + l * 128, in.gla_gain + l * 256, id * 64 + w2, id * 64 + 64, 8, l2); }
.Lqpf_skip:
	v_mov_b32_e32 v186, v214
	s_nop 0
	v_readfirstlane_b32 s6, v186
	s_ashr_i32 s57, s6, 6
	v_and_b32_e32 v187, 63, v186
	s_cmpk_gt_i32 s56, 0x2ff
	s_cbranch_scc0 .LBB0_580
	s_cmpk_gt_u32 s56, 0x31f
	s_cbranch_scc0 .LBB0_559
	s_cmpk_gt_u32 s56, 0x33f
	s_cbranch_scc0 .LBB0_529
	s_cmpk_gt_u32 s56, 0x73f
	s_cbranch_scc0 .LBB0_517
	v_cmp_eq_u32_e32 vcc, 0, v186
	s_and_saveexec_b64 s[0:1], vcc
	s_cbranch_execz .LBB0_513
	s_mov_b32 s7, 0x400001
	s_branch .LBB0_506
